# QKV GEMM workgroup stagger reduced from 12 us to 4 us per slot (both attention layers); otherwise v46
# speedup vs baseline: 1.0057x; 1.0057x over previous
; __device__ __forceinline__ void stagger_start(int slot, int us_per_slot) { const unsigned long long t0 = __builtin_amdgcn_s_memrealtime(), dt = (unsigned long long)(slot * us_per_slot) * 100ull;
;     while (__builtin_amdgcn_s_memrealtime() - t0 < dt) __builtin_amdgcn_s_sleep(32); }
; template <int L> __device__ __forceinline__ void layer_phases(Frame& F, const int lo, const int hi, const XcdBarrier& bar, const int bid) {
;     ...
;             stagger_start(bid & 3, STAG_US);
.LBB0_189:
	s_cmp_gt_i32 s56, 2
	s_cselect_b64 s[0:1], -1, 0
	s_cmp_lt_i32 s57, 3
	s_cselect_b64 s[4:5], -1, 0
	s_or_b64 s[0:1], s[0:1], s[4:5]
	s_and_b64 vcc, exec, s[0:1]
	s_cbranch_vccnz .LBB0_269
	s_add_i32 s0, 0, 0x20520
	v_mov_b32_e32 v0, s0
	ds_read_b64 v[0:1], v0
	s_memrealtime s[0:1]
	s_memrealtime s[6:7]
	s_and_b32 s3, s2, 3
	s_mov_b32 s5, 0
	s_mul_i32 s4, s3, 0x190
	s_waitcnt lgkmcnt(0)
	v_readfirstlane_b32 s16, v0
	s_sub_u32 s6, s6, s0
	v_readfirstlane_b32 s17, v1
	s_subb_u32 s7, s7, s1
	v_mov_b64_e32 v[0:1], s[4:5]
	v_cmp_ge_u64_e32 vcc, s[6:7], v[0:1]
	s_cbranch_vccnz .LBB0_193
	v_mov_b64_e32 v[0:1], s[4:5]

; __device__ __forceinline__ void stagger_start(int slot, int us_per_slot) { const unsigned long long t0 = __builtin_amdgcn_s_memrealtime(), dt = (unsigned long long)(slot * us_per_slot) * 100ull;
;     while (__builtin_amdgcn_s_memrealtime() - t0 < dt) __builtin_amdgcn_s_sleep(32); }
; template <int L> __device__ __forceinline__ void layer_phases(Frame& F, const int lo, const int hi, const XcdBarrier& bar, const int bid) {
;     ...
;             stagger_start(bid & 3, STAG_US);
.LBB0_3339:
	s_cmp_gt_i32 s56, 32
	s_cselect_b64 s[0:1], -1, 0
	s_cmp_lt_i32 s57, 33
	s_cselect_b64 s[4:5], -1, 0
	s_or_b64 s[0:1], s[0:1], s[4:5]
	s_and_b64 vcc, exec, s[0:1]
	s_cbranch_vccnz .LBB0_3419
	s_add_i32 s0, 0, 0x20520
	v_mov_b32_e32 v0, s0
	s_waitcnt lgkmcnt(0)
	ds_read_b64 v[0:1], v0
	s_memrealtime s[0:1]
	s_memrealtime s[6:7]
	s_and_b32 s3, s2, 3
	s_mov_b32 s5, 0
	s_mul_i32 s4, s3, 0x190
	s_waitcnt lgkmcnt(0)
	v_readfirstlane_b32 s16, v0
	s_sub_u32 s6, s6, s0
	v_readfirstlane_b32 s17, v1
	s_subb_u32 s7, s7, s1
	v_mov_b64_e32 v[0:1], s[4:5]
	v_cmp_ge_u64_e32 vcc, s[6:7], v[0:1]
	s_cbranch_vccnz .LBB0_3343
	v_mov_b64_e32 v[0:1], s[4:5]
